# prep diag stage (16x16 forward substitution): all triangular rows read up front with exact-width LDS reads and one wait, substitution applied column-wise (15-step dependent chain instead of 120 fmas,
# baseline (speedup 1.0000x reference)
; #define LDS_BARRIER() do { asm volatile("s_waitcnt lgkmcnt(0)" ::: "memory"); __builtin_amdgcn_s_barrier(); asm volatile("" ::: "memory"); } while (0)
; __device__ __forceinline__ void phase_dnprep(h16* Pdn, const h16* halo, const float* bd, const float* convw, const float* a_log, const float* dt_bias,
;                              h16* Tg, h16* qkg, float* gcg, float* betag, float* s2g, LAS unsigned char* ldsl, unsigned char* ldsb) {
;     ...
;         for (int e = tl; e < 4096; e += 512) { const int r = e >> 6, c = e & 63; if ((c >> 4) > (r >> 4)) X[r * 68 + c] = 0.f; }
;         LDS_BARRIER();
;         if (w < 4 && lane < 16) {
.LBB0_428:
	s_or_b64 exec, exec, s[4:5]
	s_waitcnt lgkmcnt(0)
	s_barrier
	v_cmp_gt_u32_e32 vcc, 16, v99
	s_and_b64 s[4:5], s[16:17], vcc
	s_and_saveexec_b64 s[0:1], s[4:5]
	s_cbranch_execz .LBB0_320
; __device__ __forceinline__ void phase_dnprep(h16* Pdn, const h16* halo, const float* bd, const float* convw, const float* a_log, const float* dt_bias,
;                              h16* Tg, h16* qkg, float* gcg, float* betag, float* s2g, LAS unsigned char* ldsl, unsigned char* ldsb) {
;     ...
;         if (w < 4 && lane < 16) {
;             const int q = w, c = lane;
;             float x[16];
; #pragma unroll
;             for (int i = 0; i < 16; ++i) {
;                 float mrow[16];
; #pragma unroll
;                 for (int q4 = 0; q4 < 4; ++q4) { const f32x4 t4 = *(const f32x4*)(Mm + (16 * q + i) * 68 + 16 * q + 4 * q4); mrow[4 * q4] = t4[0]; mrow[4 * q4 + 1] = t4[1]; mrow[4 * q4 + 2] = t4[2]; mrow[4 * q4 + 3] = t4[3]; }
;                 float sacc = (i == c) ? 1.f : 0.f;
; #pragma unroll
;                 for (int j = 0; j < 16; ++j) if (j < i) sacc -= mrow[j] * x[j];
;                 x[i] = sacc;
;             }
; #pragma unroll
;             for (int i = 0; i < 16; ++i) X[(16 * q + i) * 68 + 16 * q + c] = x[i];
;         }
	v_mov_b32_e32 v16, s41
	s_add_i32 s4, s78, s42
	s_add_i32 s4, s40, s4
	ds_read_b32 v112, v16 offset:272
	ds_read_b64 v[80:81], v16 offset:544
	ds_read_b96 v[196:198], v16 offset:816
	ds_read_b128 v[122:125], v16 offset:1088
	ds_read_b128 v[74:77], v16 offset:1360
	ds_read_b32 v126, v16 offset:1376
	ds_read_b128 v[176:179], v16 offset:1632
	ds_read_b64 v[180:181], v16 offset:1648
	ds_read_b128 v[114:117], v16 offset:1904
	ds_read_b96 v[118:120], v16 offset:1920
	ds_read_b128 v[102:105], v16 offset:2176
	ds_read_b128 v[106:109], v16 offset:2192
	ds_read_b128 v[4:7], v16 offset:2448
	ds_read_b128 v[8:11], v16 offset:2464
	ds_read_b32 v110, v16 offset:2480
	ds_read_b128 v[12:15], v16 offset:2720
	ds_read_b128 v[34:37], v16 offset:2736
	ds_read_b64 v[190:191], v16 offset:2752
	ds_read_b128 v[38:41], v16 offset:2992
	ds_read_b128 v[42:45], v16 offset:3008
	ds_read_b96 v[46:48], v16 offset:3024
	ds_read_b128 v[50:53], v16 offset:3264
	ds_read_b128 v[204:207], v16 offset:3280
	ds_read_b128 v[208:211], v16 offset:3296
	ds_read_b128 v[212:215], v16 offset:3536
	ds_read_b128 v[216:219], v16 offset:3552
	ds_read_b128 v[220:223], v16 offset:3568
	ds_read_b32 v199, v16 offset:3584
	ds_read_b128 v[224:227], v16 offset:3808
	ds_read_b128 v[228:231], v16 offset:3824
	ds_read_b128 v[232:235], v16 offset:3840
	ds_read_b64 v[54:55], v16 offset:3856
	ds_read_b128 v[236:239], v16 offset:4080
	ds_read_b128 v[240:243], v16 offset:4096
	ds_read_b128 v[244:247], v16 offset:4112
	ds_read_b96 v[248:250], v16 offset:4128
	v_cmp_eq_u32_e32 vcc, 0, v99
	s_nop 1
	v_cndmask_b32_e64 v17, 0, 1.0, vcc
	v_cmp_eq_u32_e32 vcc, 1, v99
	s_nop 1
	v_cndmask_b32_e64 v18, 0, 1.0, vcc
	v_cmp_eq_u32_e32 vcc, 2, v99
	s_nop 1
	v_cndmask_b32_e64 v19, 0, 1.0, vcc
	v_cmp_eq_u32_e32 vcc, 3, v99
	s_nop 1
	v_cndmask_b32_e64 v20, 0, 1.0, vcc
	v_cmp_eq_u32_e32 vcc, 4, v99
	s_nop 1
	v_cndmask_b32_e64 v21, 0, 1.0, vcc
	v_cmp_eq_u32_e32 vcc, 5, v99
	s_nop 1
	v_cndmask_b32_e64 v22, 0, 1.0, vcc
	v_cmp_eq_u32_e32 vcc, 6, v99
	s_nop 1
	v_cndmask_b32_e64 v23, 0, 1.0, vcc
	v_cmp_eq_u32_e32 vcc, 7, v99
	s_nop 1
	v_cndmask_b32_e64 v24, 0, 1.0, vcc
	v_cmp_eq_u32_e32 vcc, 8, v99
	s_nop 1
	v_cndmask_b32_e64 v25, 0, 1.0, vcc
	v_cmp_eq_u32_e32 vcc, 9, v99
	s_nop 1
	v_cndmask_b32_e64 v26, 0, 1.0, vcc
	v_cmp_eq_u32_e32 vcc, 10, v99
	s_nop 1
	v_cndmask_b32_e64 v27, 0, 1.0, vcc
	v_cmp_eq_u32_e32 vcc, 11, v99
	s_nop 1
	v_cndmask_b32_e64 v28, 0, 1.0, vcc
	v_cmp_eq_u32_e32 vcc, 12, v99
	s_nop 1
	v_cndmask_b32_e64 v29, 0, 1.0, vcc
	v_cmp_eq_u32_e32 vcc, 13, v99
	s_nop 1
	v_cndmask_b32_e64 v30, 0, 1.0, vcc
	v_cmp_eq_u32_e32 vcc, 14, v99
	s_nop 1
	v_cndmask_b32_e64 v31, 0, 1.0, vcc
	v_cmp_eq_u32_e32 vcc, 15, v99
	s_nop 1
	v_cndmask_b32_e64 v0, 0, 1.0, vcc
	s_waitcnt lgkmcnt(0)
	v_fma_f32 v18, -v112, v17, v18
	v_fma_f32 v19, -v80, v17, v19
	v_fma_f32 v20, -v196, v17, v20
	v_fma_f32 v21, -v122, v17, v21
	v_fma_f32 v22, -v74, v17, v22
	v_fma_f32 v23, -v176, v17, v23
	v_fma_f32 v24, -v114, v17, v24
	v_fma_f32 v25, -v102, v17, v25
	v_fma_f32 v26, -v4, v17, v26
	v_fma_f32 v27, -v12, v17, v27
	v_fma_f32 v28, -v38, v17, v28
	v_fma_f32 v29, -v50, v17, v29
	v_fma_f32 v30, -v212, v17, v30
	v_fma_f32 v31, -v224, v17, v31
	v_fma_f32 v0, -v236, v17, v0
	v_fma_f32 v19, -v81, v18, v19
	v_fma_f32 v20, -v197, v18, v20
	v_fma_f32 v21, -v123, v18, v21
	v_fma_f32 v22, -v75, v18, v22
	v_fma_f32 v23, -v177, v18, v23
	v_fma_f32 v24, -v115, v18, v24
	v_fma_f32 v25, -v103, v18, v25
	v_fma_f32 v26, -v5, v18, v26
	v_fma_f32 v27, -v13, v18, v27
	v_fma_f32 v28, -v39, v18, v28
	v_fma_f32 v29, -v51, v18, v29
	v_fma_f32 v30, -v213, v18, v30
	v_fma_f32 v31, -v225, v18, v31
	v_fma_f32 v0, -v237, v18, v0
	v_fma_f32 v20, -v198, v19, v20
	v_fma_f32 v21, -v124, v19, v21
	v_fma_f32 v22, -v76, v19, v22
	v_fma_f32 v23, -v178, v19, v23
	v_fma_f32 v24, -v116, v19, v24
	v_fma_f32 v25, -v104, v19, v25
	v_fma_f32 v26, -v6, v19, v26
	v_fma_f32 v27, -v14, v19, v27
	v_fma_f32 v28, -v40, v19, v28
	v_fma_f32 v29, -v52, v19, v29
	v_fma_f32 v30, -v214, v19, v30
	v_fma_f32 v31, -v226, v19, v31
	v_fma_f32 v0, -v238, v19, v0
	v_fma_f32 v21, -v125, v20, v21
	v_fma_f32 v22, -v77, v20, v22
	v_fma_f32 v23, -v179, v20, v23
	v_fma_f32 v24, -v117, v20, v24
	v_fma_f32 v25, -v105, v20, v25
	v_fma_f32 v26, -v7, v20, v26
	v_fma_f32 v27, -v15, v20, v27
	v_fma_f32 v28, -v41, v20, v28
	v_fma_f32 v29, -v53, v20, v29
	v_fma_f32 v30, -v215, v20, v30
	v_fma_f32 v31, -v227, v20, v31
	v_fma_f32 v0, -v239, v20, v0
	v_fma_f32 v22, -v126, v21, v22
	v_fma_f32 v23, -v180, v21, v23
	v_fma_f32 v24, -v118, v21, v24
	v_fma_f32 v25, -v106, v21, v25
	v_fma_f32 v26, -v8, v21, v26
	v_fma_f32 v27, -v34, v21, v27
	v_fma_f32 v28, -v42, v21, v28
	v_fma_f32 v29, -v204, v21, v29
	v_fma_f32 v30, -v216, v21, v30
	v_fma_f32 v31, -v228, v21, v31
	v_fma_f32 v0, -v240, v21, v0
	v_fma_f32 v23, -v181, v22, v23
	v_fma_f32 v24, -v119, v22, v24
	v_fma_f32 v25, -v107, v22, v25
	v_fma_f32 v26, -v9, v22, v26
	v_fma_f32 v27, -v35, v22, v27
	v_fma_f32 v28, -v43, v22, v28
	v_fma_f32 v29, -v205, v22, v29
	v_fma_f32 v30, -v217, v22, v30
	v_fma_f32 v31, -v229, v22, v31
	v_fma_f32 v0, -v241, v22, v0
	v_fma_f32 v24, -v120, v23, v24
	v_fma_f32 v25, -v108, v23, v25
	v_fma_f32 v26, -v10, v23, v26
	v_fma_f32 v27, -v36, v23, v27
	v_fma_f32 v28, -v44, v23, v28
	v_fma_f32 v29, -v206, v23, v29
	v_fma_f32 v30, -v218, v23, v30
	v_fma_f32 v31, -v230, v23, v31
	v_fma_f32 v0, -v242, v23, v0
	v_fma_f32 v25, -v109, v24, v25
	v_fma_f32 v26, -v11, v24, v26
	v_fma_f32 v27, -v37, v24, v27
	v_fma_f32 v28, -v45, v24, v28
	v_fma_f32 v29, -v207, v24, v29
	v_fma_f32 v30, -v219, v24, v30
	v_fma_f32 v31, -v231, v24, v31
	v_fma_f32 v0, -v243, v24, v0
	v_fma_f32 v26, -v110, v25, v26
	v_fma_f32 v27, -v190, v25, v27
	v_fma_f32 v28, -v46, v25, v28
	v_fma_f32 v29, -v208, v25, v29
	v_fma_f32 v30, -v220, v25, v30
	v_fma_f32 v31, -v232, v25, v31
	v_fma_f32 v0, -v244, v25, v0
	v_fma_f32 v27, -v191, v26, v27
	v_fma_f32 v28, -v47, v26, v28
	v_fma_f32 v29, -v209, v26, v29
	v_fma_f32 v30, -v221, v26, v30
	v_fma_f32 v31, -v233, v26, v31
	v_fma_f32 v0, -v245, v26, v0
	v_fma_f32 v28, -v48, v27, v28
	v_fma_f32 v29, -v210, v27, v29
	v_fma_f32 v30, -v222, v27, v30
	v_fma_f32 v31, -v234, v27, v31
	v_fma_f32 v0, -v246, v27, v0
	v_fma_f32 v29, -v211, v28, v29
	v_fma_f32 v30, -v223, v28, v30
	v_fma_f32 v31, -v235, v28, v31
	v_fma_f32 v0, -v247, v28, v0
	v_fma_f32 v30, -v199, v29, v30
	v_fma_f32 v31, -v54, v29, v31
	v_fma_f32 v0, -v248, v29, v0
	v_fma_f32 v31, -v55, v30, v31
	v_fma_f32 v0, -v249, v30, v0
	v_fma_f32 v0, -v250, v31, v0
	v_lshl_add_u32 v1, v99, 2, s4
	v_add_u32_e32 v2, 0x400, v1
	ds_write2_b32 v1, v17, v18 offset1:68
	ds_write2_b32 v1, v19, v20 offset0:136 offset1:204
	ds_write2_b32 v2, v21, v22 offset0:16 offset1:84
	ds_write2_b32 v2, v23, v24 offset0:152 offset1:220
	v_add_u32_e32 v2, 0x800, v1
	v_add_u32_e32 v1, 0xc00, v1
	ds_write2_b32 v2, v25, v26 offset0:32 offset1:100
	ds_write2_b32 v2, v27, v28 offset0:168 offset1:236
	ds_write2_b32 v1, v29, v30 offset0:48 offset1:116
	ds_write2_b32 v1, v31, v0 offset0:184 offset1:252
	s_branch .LBB0_320
